# rowpass0 no longer copies the latent input rows into the working residual buffer; layer 0's w_o residual epilogue reads x from the input tensor (67 MB fewer writes)
# speedup vs baseline: 1.0110x; 1.0110x over previous
.LBB0_135:
	v_mul_hi_i32 v0, v16, s26
	v_lshrrev_b32_e32 v1, 31, v0
	v_ashrrev_i32_e32 v0, 11, v0
	v_add_u32_e32 v23, v0, v1
	v_mul_i32_i24_e32 v0, 0xffffdf00, v23
	v_mad_i32_i24 v2, v23, s27, v16
	v_lshl_add_u32 v1, v23, 13, v0
	v_cmp_gt_i32_e64 s[2:3], s24, v2
	v_cmp_lt_i32_e64 s[4:5], s28, v2
	v_add3_u32 v0, v16, v1, s29
	s_and_saveexec_b64 s[20:21], s[4:5]
	s_xor_b64 s[20:21], exec, s[20:21]
	s_load_dwordx2 s[22:23], s[0:1], 0xe8
	v_add3_u32 v28, v16, v1, s29
	s_or_saveexec_b64 s[20:21], s[20:21]
	s_waitcnt lgkmcnt(0)
	v_mov_b64_e32 v[32:33], s[22:23]
	v_lshl_add_u32 v1, v23, 8, v2
	s_xor_b64 exec, exec, s[20:21]
	v_lshl_add_u32 v28, v23, 8, v2
	v_mov_b64_e32 v[32:33], s[10:11]
	s_or_b64 exec, exec, s[20:21]
	s_and_saveexec_b64 s[20:21], s[4:5]
	s_xor_b64 s[4:5], exec, s[20:21]
	s_or_saveexec_b64 s[4:5], s[4:5]
	v_mov_b32_e32 v30, 1.0
	v_mov_b64_e32 v[2:3], s[0:1]
	s_xor_b64 exec, exec, s[4:5]
	v_mov_b32_e32 v30, 0x3fb504f3
	v_mov_b64_e32 v[2:3], s[12:13]
	v_mov_b32_e32 v0, v1
	s_or_b64 exec, exec, s[4:5]
	global_load_dwordx2 v[2:3], v[2:3], off
	v_ashrrev_i32_e32 v1, 31, v0
	v_lshlrev_b64 v[0:1], 12, v[0:1]
	v_ashrrev_i32_e32 v29, 31, v28
	v_lshlrev_b64 v[28:29], 12, v[28:29]
	v_lshl_add_u64 v[28:29], v[32:33], 0, v[28:29]
	v_lshl_add_u64 v[28:29], v[28:29], 0, v[18:19]
	v_ashrrev_i32_e32 v17, 31, v16
	s_waitcnt vmcnt(0)
	v_lshl_add_u64 v[0:1], v[2:3], 0, v[0:1]
	v_lshl_add_u64 v[34:35], v[0:1], 0, v[18:19]
	global_load_dwordx4 v[12:15], v[34:35], off
	global_load_dwordx4 v[8:11], v[34:35], off offset:1024
	global_load_dwordx4 v[4:7], v[34:35], off offset:2048
	global_load_dwordx4 v[0:3], v[34:35], off offset:3072
	s_waitcnt vmcnt(3)
	v_pk_mul_f32 v[34:35], v[30:31], v[14:15] op_sel_hi:[0,1]
	v_pk_mul_f32 v[32:33], v[30:31], v[12:13] op_sel_hi:[0,1]
	s_waitcnt vmcnt(2)
	v_pk_mul_f32 v[38:39], v[30:31], v[10:11] op_sel_hi:[0,1]
	v_pk_mul_f32 v[36:37], v[30:31], v[8:9] op_sel_hi:[0,1]
	s_waitcnt vmcnt(1)
	v_pk_mul_f32 v[42:43], v[30:31], v[6:7] op_sel_hi:[0,1]
	v_pk_mul_f32 v[40:41], v[30:31], v[4:5] op_sel_hi:[0,1]
	s_waitcnt vmcnt(0)
	v_pk_mul_f32 v[46:47], v[30:31], v[2:3] op_sel_hi:[0,1]
	v_pk_mul_f32 v[44:45], v[30:31], v[0:1] op_sel_hi:[0,1]
	s_cmp_eq_u64 s[2:3], 0
	s_cbranch_scc1 .Lrp0_nocopy
	global_store_dwordx4 v[28:29], v[32:35], off
	global_store_dwordx4 v[28:29], v[36:39], off offset:1024
	global_store_dwordx4 v[28:29], v[40:43], off offset:2048
	global_store_dwordx4 v[28:29], v[44:47], off offset:3072
.Lrp0_nocopy:
	s_and_saveexec_b64 s[4:5], vcc
	s_cbranch_execz .LBB0_134
	v_mov_b32_e32 v32, v19
	v_lshl_add_u64 v[28:29], v[16:17], 3, s[14:15]
	s_nop 0
	v_mov_b32_e32 v33, v32
	global_store_dwordx2 v[28:29], v[32:33], off
	s_branch .LBB0_134

.LBB0_662:
	s_or_b64 exec, exec, s[0:1]
	s_mul_hi_i32 s0, s10, 0x3e0f83e1
	s_lshr_b32 s1, s0, 31
	s_ashr_i32 s0, s0, 3
	s_add_i32 s0, s0, s1
	s_mul_hi_i32 s1, s0, 0x6000
	s_mulk_i32 s0, 0x6000
	s_add_u32 s0, s14, s0
	s_addc_u32 s1, s15, s1
	s_add_u32 s10, s0, 0x2000
	v_or_b32_e32 v136, s12, v143
	s_addc_u32 s11, s1, 0
	v_lshlrev_b32_e32 v132, 2, v136
	s_waitcnt lgkmcnt(0)
	s_barrier
	global_load_dwordx4 v[128:131], v132, s[10:11] offset:16
	s_nop 0
	global_load_dwordx4 v[132:135], v132, s[10:11]
	v_add_u32_e32 v137, s13, v144
	s_load_dwordx2 s[24:25], s[40:41], 0xe8
	s_load_dwordx2 s[28:29], s[40:41], 0x0
	v_lshlrev_b32_e32 v176, 2, v136
	v_lshrrev_b32_e32 v249, 13, v137
	v_min_u32_e32 v249, 1, v249
	v_lshlrev_b32_e32 v249, 8, v249
	v_sub_u32_e32 v249, v137, v249
	v_lshlrev_b32_e32 v249, 12, v249
	v_lshl_add_u32 v249, v136, 2, v249
	v_add_u32_e32 v248, 0x10000, v145
	s_waitcnt lgkmcnt(0)
	s_add_u32 s26, s24, 0x80000
	s_addc_u32 s27, s25, 0
	s_cmp_lg_u64 s[60:61], 0
	s_cselect_b32 s28, s28, s24
	s_cselect_b32 s29, s29, s25
	s_add_u32 s30, s28, 0x80000
	s_addc_u32 s31, s29, 0
	v_mov_b32_e32 v254, v249
	v_add_u32_e32 v253, 0x20000, v249
	v_add_u32_e32 v251, 0x40000, v249
	v_add_u32_e32 v250, 0x60000, v249
	global_load_dwordx4 v[138:141], v254, s[28:29]
	global_load_dwordx4 v[154:157], v254, s[28:29] offset:16
	global_load_dwordx4 v[158:161], v253, s[28:29]
	global_load_dwordx4 v[162:165], v253, s[28:29] offset:16
	global_load_dwordx4 v[166:169], v251, s[28:29]
	global_load_dwordx4 v[170:173], v251, s[28:29] offset:16
	global_load_dwordx4 v[178:181], v250, s[28:29]
	global_load_dwordx4 v[182:185], v250, s[28:29] offset:16
	global_load_dwordx4 v[186:189], v254, s[30:31]
	global_load_dwordx4 v[192:195], v254, s[30:31] offset:16
	global_load_dwordx4 v[198:201], v253, s[30:31]
	global_load_dwordx4 v[204:207], v253, s[30:31] offset:16
	global_load_dwordx4 v[208:211], v251, s[30:31]
	global_load_dwordx4 v[212:215], v251, s[30:31] offset:16
	global_load_dwordx4 v[216:219], v250, s[30:31]
	global_load_dwordx4 v[220:223], v250, s[30:31] offset:16
	ds_read_b128 v[224:227], v145
	ds_read_b128 v[228:231], v145 offset:16
	ds_read_b128 v[232:235], v145 offset:16384
	ds_read_b128 v[236:239], v145 offset:16400
	s_waitcnt vmcnt(14)
	v_pk_mul_f32 v[140:141], v[140:141], s[34:35] op_sel_hi:[1,0]
	v_pk_mul_f32 v[138:139], v[138:139], s[34:35] op_sel_hi:[1,0]
	v_pk_mul_f32 v[156:157], v[156:157], s[34:35] op_sel_hi:[1,0]
	v_pk_mul_f32 v[154:155], v[154:155], s[34:35] op_sel_hi:[1,0]
	s_waitcnt lgkmcnt(2)
	v_pk_fma_f32 v[140:141], v[134:135], v[226:227], v[140:141]
	v_pk_fma_f32 v[138:139], v[132:133], v[224:225], v[138:139]
	v_pk_fma_f32 v[156:157], v[130:131], v[230:231], v[156:157]
	v_pk_fma_f32 v[154:155], v[128:129], v[228:229], v[154:155]
	ds_read_b128 v[224:227], v145 offset:32768
	ds_read_b128 v[228:231], v145 offset:32784
	global_store_dwordx4 v254, v[138:141], s[24:25]
	global_store_dwordx4 v254, v[154:157], s[24:25] offset:16
	s_waitcnt vmcnt(14)
	v_pk_mul_f32 v[160:161], v[160:161], s[34:35] op_sel_hi:[1,0]
	v_pk_mul_f32 v[158:159], v[158:159], s[34:35] op_sel_hi:[1,0]
	v_pk_mul_f32 v[164:165], v[164:165], s[34:35] op_sel_hi:[1,0]
	v_pk_mul_f32 v[162:163], v[162:163], s[34:35] op_sel_hi:[1,0]
	s_waitcnt lgkmcnt(2)
	v_pk_fma_f32 v[160:161], v[134:135], v[234:235], v[160:161]
	v_pk_fma_f32 v[158:159], v[132:133], v[232:233], v[158:159]
	v_pk_fma_f32 v[164:165], v[130:131], v[238:239], v[164:165]
	v_pk_fma_f32 v[162:163], v[128:129], v[236:237], v[162:163]
	ds_read_b128 v[232:235], v145 offset:49152
	ds_read_b128 v[236:239], v145 offset:49168
	global_store_dwordx4 v253, v[158:161], s[24:25]
	global_store_dwordx4 v253, v[162:165], s[24:25] offset:16
	s_waitcnt vmcnt(14)
	v_pk_mul_f32 v[168:169], v[168:169], s[34:35] op_sel_hi:[1,0]
	v_pk_mul_f32 v[166:167], v[166:167], s[34:35] op_sel_hi:[1,0]
	v_pk_mul_f32 v[172:173], v[172:173], s[34:35] op_sel_hi:[1,0]
	v_pk_mul_f32 v[170:171], v[170:171], s[34:35] op_sel_hi:[1,0]
	s_waitcnt lgkmcnt(2)
	v_pk_fma_f32 v[168:169], v[134:135], v[226:227], v[168:169]
	v_pk_fma_f32 v[166:167], v[132:133], v[224:225], v[166:167]
	v_pk_fma_f32 v[172:173], v[130:131], v[230:231], v[172:173]
	v_pk_fma_f32 v[170:171], v[128:129], v[228:229], v[170:171]
	ds_read_b128 v[224:227], v248
	ds_read_b128 v[228:231], v248 offset:16
	global_store_dwordx4 v251, v[166:169], s[24:25]
	global_store_dwordx4 v251, v[170:173], s[24:25] offset:16
	s_waitcnt vmcnt(14)
	v_pk_mul_f32 v[180:181], v[180:181], s[34:35] op_sel_hi:[1,0]
	v_pk_mul_f32 v[178:179], v[178:179], s[34:35] op_sel_hi:[1,0]
	v_pk_mul_f32 v[184:185], v[184:185], s[34:35] op_sel_hi:[1,0]
	v_pk_mul_f32 v[182:183], v[182:183], s[34:35] op_sel_hi:[1,0]
	s_waitcnt lgkmcnt(2)
	v_pk_fma_f32 v[180:181], v[134:135], v[234:235], v[180:181]
	v_pk_fma_f32 v[178:179], v[132:133], v[232:233], v[178:179]
	v_pk_fma_f32 v[184:185], v[130:131], v[238:239], v[184:185]
	v_pk_fma_f32 v[182:183], v[128:129], v[236:237], v[182:183]
	ds_read_b128 v[232:235], v248 offset:16384
	ds_read_b128 v[236:239], v248 offset:16400
	global_store_dwordx4 v250, v[178:181], s[24:25]
	global_store_dwordx4 v250, v[182:185], s[24:25] offset:16
	s_waitcnt vmcnt(14)
	v_pk_mul_f32 v[188:189], v[188:189], s[34:35] op_sel_hi:[1,0]
	v_pk_mul_f32 v[186:187], v[186:187], s[34:35] op_sel_hi:[1,0]
	v_pk_mul_f32 v[194:195], v[194:195], s[34:35] op_sel_hi:[1,0]
	v_pk_mul_f32 v[192:193], v[192:193], s[34:35] op_sel_hi:[1,0]
	s_waitcnt lgkmcnt(2)
	v_pk_fma_f32 v[188:189], v[134:135], v[226:227], v[188:189]
	v_pk_fma_f32 v[186:187], v[132:133], v[224:225], v[186:187]
	v_pk_fma_f32 v[194:195], v[130:131], v[230:231], v[194:195]
	v_pk_fma_f32 v[192:193], v[128:129], v[228:229], v[192:193]
	ds_read_b128 v[224:227], v248 offset:32768
	ds_read_b128 v[228:231], v248 offset:32784
	global_store_dwordx4 v254, v[186:189], s[26:27]
	global_store_dwordx4 v254, v[192:195], s[26:27] offset:16
	s_waitcnt vmcnt(14)
	v_pk_mul_f32 v[200:201], v[200:201], s[34:35] op_sel_hi:[1,0]
	v_pk_mul_f32 v[198:199], v[198:199], s[34:35] op_sel_hi:[1,0]
	v_pk_mul_f32 v[206:207], v[206:207], s[34:35] op_sel_hi:[1,0]
	v_pk_mul_f32 v[204:205], v[204:205], s[34:35] op_sel_hi:[1,0]
	s_waitcnt lgkmcnt(2)
	v_pk_fma_f32 v[200:201], v[134:135], v[234:235], v[200:201]
	v_pk_fma_f32 v[198:199], v[132:133], v[232:233], v[198:199]
	v_pk_fma_f32 v[206:207], v[130:131], v[238:239], v[206:207]
	v_pk_fma_f32 v[204:205], v[128:129], v[236:237], v[204:205]
	ds_read_b128 v[232:235], v248 offset:49152
	ds_read_b128 v[236:239], v248 offset:49168
	global_store_dwordx4 v253, v[198:201], s[26:27]
	global_store_dwordx4 v253, v[204:207], s[26:27] offset:16
	s_waitcnt vmcnt(14)
	v_pk_mul_f32 v[210:211], v[210:211], s[34:35] op_sel_hi:[1,0]
	v_pk_mul_f32 v[208:209], v[208:209], s[34:35] op_sel_hi:[1,0]
	v_pk_mul_f32 v[214:215], v[214:215], s[34:35] op_sel_hi:[1,0]
	v_pk_mul_f32 v[212:213], v[212:213], s[34:35] op_sel_hi:[1,0]
	s_waitcnt lgkmcnt(2)
	v_pk_fma_f32 v[210:211], v[134:135], v[226:227], v[210:211]
	v_pk_fma_f32 v[208:209], v[132:133], v[224:225], v[208:209]
	v_pk_fma_f32 v[214:215], v[130:131], v[230:231], v[214:215]
	v_pk_fma_f32 v[212:213], v[128:129], v[228:229], v[212:213]
	global_store_dwordx4 v251, v[208:211], s[26:27]
	global_store_dwordx4 v251, v[212:215], s[26:27] offset:16
	s_waitcnt vmcnt(14)
	v_pk_mul_f32 v[218:219], v[218:219], s[34:35] op_sel_hi:[1,0]
	v_pk_mul_f32 v[216:217], v[216:217], s[34:35] op_sel_hi:[1,0]
	v_pk_mul_f32 v[222:223], v[222:223], s[34:35] op_sel_hi:[1,0]
	v_pk_mul_f32 v[220:221], v[220:221], s[34:35] op_sel_hi:[1,0]
	s_waitcnt lgkmcnt(0)
	v_pk_fma_f32 v[218:219], v[134:135], v[234:235], v[218:219]
	v_pk_fma_f32 v[216:217], v[132:133], v[232:233], v[216:217]
	v_pk_fma_f32 v[222:223], v[130:131], v[238:239], v[222:223]
	v_pk_fma_f32 v[220:221], v[128:129], v[236:237], v[220:221]
	global_store_dwordx4 v250, v[216:219], s[26:27]
	global_store_dwordx4 v250, v[220:223], s[26:27] offset:16

.LBB0_674:
	s_or_b64 exec, exec, s[0:1]
	v_lshl_or_b32 v4, v136, 2, v191
	s_waitcnt lgkmcnt(0)
	s_barrier
	global_load_dwordx4 v[0:3], v4, s[10:11] offset:16
	s_nop 0
	global_load_dwordx4 v[4:7], v4, s[10:11]
	s_load_dwordx2 s[24:25], s[40:41], 0xe8
	s_load_dwordx2 s[28:29], s[40:41], 0x0
	v_lshlrev_b32_e32 v176, 2, v136
	v_lshrrev_b32_e32 v249, 13, v137
	v_min_u32_e32 v249, 1, v249
	v_lshlrev_b32_e32 v249, 8, v249
	v_sub_u32_e32 v249, v137, v249
	v_lshlrev_b32_e32 v249, 12, v249
	v_lshl_add_u32 v249, v136, 2, v249
	v_add_u32_e32 v248, 0x10000, v145
	s_waitcnt lgkmcnt(0)
	s_add_u32 s26, s24, 0x80000
	s_addc_u32 s27, s25, 0
	s_cmp_lg_u64 s[60:61], 0
	s_cselect_b32 s28, s28, s24
	s_cselect_b32 s29, s29, s25
	s_add_u32 s30, s28, 0x80000
	s_addc_u32 s31, s29, 0
	v_mov_b32_e32 v254, v249
	v_add_u32_e32 v253, 0x20000, v249
	v_add_u32_e32 v251, 0x40000, v249
	v_add_u32_e32 v250, 0x60000, v249
	global_load_dwordx4 v[8:11], v254, s[28:29] offset:512
	global_load_dwordx4 v[12:15], v254, s[28:29] offset:528
	global_load_dwordx4 v[16:19], v253, s[28:29] offset:512
	global_load_dwordx4 v[20:23], v253, s[28:29] offset:528
	global_load_dwordx4 v[24:27], v251, s[28:29] offset:512
	global_load_dwordx4 v[170:173], v251, s[28:29] offset:528
	global_load_dwordx4 v[178:181], v250, s[28:29] offset:512
	global_load_dwordx4 v[182:185], v250, s[28:29] offset:528
	global_load_dwordx4 v[186:189], v254, s[30:31] offset:512
	global_load_dwordx4 v[192:195], v254, s[30:31] offset:528
	global_load_dwordx4 v[198:201], v253, s[30:31] offset:512
	global_load_dwordx4 v[204:207], v253, s[30:31] offset:528
	global_load_dwordx4 v[208:211], v251, s[30:31] offset:512
	global_load_dwordx4 v[212:215], v251, s[30:31] offset:528
	global_load_dwordx4 v[216:219], v250, s[30:31] offset:512
	global_load_dwordx4 v[220:223], v250, s[30:31] offset:528
	ds_read_b128 v[224:227], v145
	ds_read_b128 v[228:231], v145 offset:16
	ds_read_b128 v[232:235], v145 offset:16384
	ds_read_b128 v[236:239], v145 offset:16400
	s_waitcnt vmcnt(14)
	v_pk_mul_f32 v[10:11], v[10:11], s[34:35] op_sel_hi:[1,0]
	v_pk_mul_f32 v[8:9], v[8:9], s[34:35] op_sel_hi:[1,0]
	v_pk_mul_f32 v[14:15], v[14:15], s[34:35] op_sel_hi:[1,0]
	v_pk_mul_f32 v[12:13], v[12:13], s[34:35] op_sel_hi:[1,0]
	s_waitcnt lgkmcnt(2)
	v_pk_fma_f32 v[10:11], v[6:7], v[226:227], v[10:11]
	v_pk_fma_f32 v[8:9], v[4:5], v[224:225], v[8:9]
	v_pk_fma_f32 v[14:15], v[2:3], v[230:231], v[14:15]
	v_pk_fma_f32 v[12:13], v[0:1], v[228:229], v[12:13]
	ds_read_b128 v[224:227], v145 offset:32768
	ds_read_b128 v[228:231], v145 offset:32784
	global_store_dwordx4 v254, v[8:11], s[24:25] offset:512
	global_store_dwordx4 v254, v[12:15], s[24:25] offset:528
	s_waitcnt vmcnt(14)
	v_pk_mul_f32 v[18:19], v[18:19], s[34:35] op_sel_hi:[1,0]
	v_pk_mul_f32 v[16:17], v[16:17], s[34:35] op_sel_hi:[1,0]
	v_pk_mul_f32 v[22:23], v[22:23], s[34:35] op_sel_hi:[1,0]
	v_pk_mul_f32 v[20:21], v[20:21], s[34:35] op_sel_hi:[1,0]
	s_waitcnt lgkmcnt(2)
	v_pk_fma_f32 v[18:19], v[6:7], v[234:235], v[18:19]
	v_pk_fma_f32 v[16:17], v[4:5], v[232:233], v[16:17]
	v_pk_fma_f32 v[22:23], v[2:3], v[238:239], v[22:23]
	v_pk_fma_f32 v[20:21], v[0:1], v[236:237], v[20:21]
	ds_read_b128 v[232:235], v145 offset:49152
	ds_read_b128 v[236:239], v145 offset:49168
	global_store_dwordx4 v253, v[16:19], s[24:25] offset:512
	global_store_dwordx4 v253, v[20:23], s[24:25] offset:528
	s_waitcnt vmcnt(14)
	v_pk_mul_f32 v[26:27], v[26:27], s[34:35] op_sel_hi:[1,0]
	v_pk_mul_f32 v[24:25], v[24:25], s[34:35] op_sel_hi:[1,0]
	v_pk_mul_f32 v[172:173], v[172:173], s[34:35] op_sel_hi:[1,0]
	v_pk_mul_f32 v[170:171], v[170:171], s[34:35] op_sel_hi:[1,0]
	s_waitcnt lgkmcnt(2)
	v_pk_fma_f32 v[26:27], v[6:7], v[226:227], v[26:27]
	v_pk_fma_f32 v[24:25], v[4:5], v[224:225], v[24:25]
	v_pk_fma_f32 v[172:173], v[2:3], v[230:231], v[172:173]
	v_pk_fma_f32 v[170:171], v[0:1], v[228:229], v[170:171]
	ds_read_b128 v[224:227], v248
	ds_read_b128 v[228:231], v248 offset:16
	global_store_dwordx4 v251, v[24:27], s[24:25] offset:512
	global_store_dwordx4 v251, v[170:173], s[24:25] offset:528
	s_waitcnt vmcnt(14)
	v_pk_mul_f32 v[180:181], v[180:181], s[34:35] op_sel_hi:[1,0]
	v_pk_mul_f32 v[178:179], v[178:179], s[34:35] op_sel_hi:[1,0]
	v_pk_mul_f32 v[184:185], v[184:185], s[34:35] op_sel_hi:[1,0]
	v_pk_mul_f32 v[182:183], v[182:183], s[34:35] op_sel_hi:[1,0]
	s_waitcnt lgkmcnt(2)
	v_pk_fma_f32 v[180:181], v[6:7], v[234:235], v[180:181]
	v_pk_fma_f32 v[178:179], v[4:5], v[232:233], v[178:179]
	v_pk_fma_f32 v[184:185], v[2:3], v[238:239], v[184:185]
	v_pk_fma_f32 v[182:183], v[0:1], v[236:237], v[182:183]
	ds_read_b128 v[232:235], v248 offset:16384
	ds_read_b128 v[236:239], v248 offset:16400
	global_store_dwordx4 v250, v[178:181], s[24:25] offset:512
	global_store_dwordx4 v250, v[182:185], s[24:25] offset:528
	s_waitcnt vmcnt(14)
	v_pk_mul_f32 v[188:189], v[188:189], s[34:35] op_sel_hi:[1,0]
	v_pk_mul_f32 v[186:187], v[186:187], s[34:35] op_sel_hi:[1,0]
	v_pk_mul_f32 v[194:195], v[194:195], s[34:35] op_sel_hi:[1,0]
	v_pk_mul_f32 v[192:193], v[192:193], s[34:35] op_sel_hi:[1,0]
	s_waitcnt lgkmcnt(2)
	v_pk_fma_f32 v[188:189], v[6:7], v[226:227], v[188:189]
	v_pk_fma_f32 v[186:187], v[4:5], v[224:225], v[186:187]
	v_pk_fma_f32 v[194:195], v[2:3], v[230:231], v[194:195]
	v_pk_fma_f32 v[192:193], v[0:1], v[228:229], v[192:193]
	ds_read_b128 v[224:227], v248 offset:32768
	ds_read_b128 v[228:231], v248 offset:32784
	global_store_dwordx4 v254, v[186:189], s[26:27] offset:512
	global_store_dwordx4 v254, v[192:195], s[26:27] offset:528
	s_waitcnt vmcnt(14)
	v_pk_mul_f32 v[200:201], v[200:201], s[34:35] op_sel_hi:[1,0]
	v_pk_mul_f32 v[198:199], v[198:199], s[34:35] op_sel_hi:[1,0]
	v_pk_mul_f32 v[206:207], v[206:207], s[34:35] op_sel_hi:[1,0]
	v_pk_mul_f32 v[204:205], v[204:205], s[34:35] op_sel_hi:[1,0]
	s_waitcnt lgkmcnt(2)
	v_pk_fma_f32 v[200:201], v[6:7], v[234:235], v[200:201]
	v_pk_fma_f32 v[198:199], v[4:5], v[232:233], v[198:199]
	v_pk_fma_f32 v[206:207], v[2:3], v[238:239], v[206:207]
	v_pk_fma_f32 v[204:205], v[0:1], v[236:237], v[204:205]
	ds_read_b128 v[232:235], v248 offset:49152
	ds_read_b128 v[236:239], v248 offset:49168
	global_store_dwordx4 v253, v[198:201], s[26:27] offset:512
	global_store_dwordx4 v253, v[204:207], s[26:27] offset:528
	s_waitcnt vmcnt(14)
	v_pk_mul_f32 v[210:211], v[210:211], s[34:35] op_sel_hi:[1,0]
	v_pk_mul_f32 v[208:209], v[208:209], s[34:35] op_sel_hi:[1,0]
	v_pk_mul_f32 v[214:215], v[214:215], s[34:35] op_sel_hi:[1,0]
	v_pk_mul_f32 v[212:213], v[212:213], s[34:35] op_sel_hi:[1,0]
	s_waitcnt lgkmcnt(2)
	v_pk_fma_f32 v[210:211], v[6:7], v[226:227], v[210:211]
	v_pk_fma_f32 v[208:209], v[4:5], v[224:225], v[208:209]
	v_pk_fma_f32 v[214:215], v[2:3], v[230:231], v[214:215]
	v_pk_fma_f32 v[212:213], v[0:1], v[228:229], v[212:213]
	global_store_dwordx4 v251, v[208:211], s[26:27] offset:512
	global_store_dwordx4 v251, v[212:215], s[26:27] offset:528
	s_waitcnt vmcnt(14)
	v_pk_mul_f32 v[218:219], v[218:219], s[34:35] op_sel_hi:[1,0]
	v_pk_mul_f32 v[216:217], v[216:217], s[34:35] op_sel_hi:[1,0]
	v_pk_mul_f32 v[222:223], v[222:223], s[34:35] op_sel_hi:[1,0]
	v_pk_mul_f32 v[220:221], v[220:221], s[34:35] op_sel_hi:[1,0]
	s_waitcnt lgkmcnt(0)
	v_pk_fma_f32 v[218:219], v[6:7], v[234:235], v[218:219]
	v_pk_fma_f32 v[216:217], v[4:5], v[232:233], v[216:217]
	v_pk_fma_f32 v[222:223], v[2:3], v[238:239], v[222:223]
	v_pk_fma_f32 v[220:221], v[0:1], v[236:237], v[220:221]
	global_store_dwordx4 v250, v[216:219], s[26:27] offset:512
	global_store_dwordx4 v250, v[220:223], s[26:27] offset:528
	s_branch .LBB0_655
